# v15 plus code placement pin: GEMM K-loop bodies and the attention steady-state loop heads padded to 64-byte boundaries
# speedup vs baseline: 1.0009x; 1.0009x over previous
; template <class Epi, class Sched, bool ALIGN_EPI = false, bool SP2 = false>
; __device__ __forceinline__ void gemm_phase(PG8_LAS unsigned char* lds, const Gemm g, const Sched& S, const Epi& E, const int wave_s) {
;     ...
;         const bool has_next = S.next(ui + 1, nxt);
;         const char* nA = has_next ? (const char*)g.A + (size_t)nxt.pm * tA : cA; const char* nB = has_next ? (const char*)g.Bt + (size_t)nxt.pn * tB : cB;
;     ...
; #pragma unroll
;         for (int a = 0; a < 2; ++a)
; #pragma unroll
;             for (int b = 0; b < 2; ++b)
; #pragma unroll
;                 for (int m = 0; m < 4; ++m)
; #pragma unroll
;                     for (int n = 0; n < 2; ++n) acc[a][b][m][n] = (f32x4){0.f, 0.f, 0.f, 0.f};
;         cur = nxt; cA = nA; cB = nB; ++ui;
.LBB0_203:
	s_ashr_i32 s65, s64, 31
	s_lshl_b64 s[8:9], s[64:65], 19
	s_add_u32 s66, s24, s8
	s_addc_u32 s67, s25, s9
	s_and_b64 s[8:9], s[2:3], exec
	s_cselect_b32 s5, s67, s7
	s_cselect_b32 s8, s66, s6
	s_ashr_i32 s63, s62, 31
	s_lshl_b64 s[12:13], s[62:63], 19
	s_add_u32 s68, s60, s12
	s_addc_u32 s69, s61, s13
	s_and_b64 s[12:13], s[2:3], exec
	s_cselect_b32 s9, s69, s73
	s_cselect_b32 s12, s68, s72
	s_lshl_b32 s11, s4, 8
	v_add_u32_e32 v0, s11, v184
	s_add_u32 s6, s6, 0x40080
	v_ashrrev_i32_e32 v1, 31, v0
	s_addc_u32 s7, s7, 0
	v_lshl_add_u64 v[112:113], v[0:1], 2, s[40:41]
	s_add_u32 s13, s72, 0x100
	v_mov_b32_e32 v0, 0
	s_addc_u32 s34, s73, 0
	s_mov_b32 s35, -2
	v_mov_b32_e32 v1, v0
	v_mov_b32_e32 v2, v0
	v_mov_b32_e32 v3, v0
	v_mov_b32_e32 v4, v0
	v_mov_b32_e32 v5, v0
	v_mov_b32_e32 v6, v0
	v_mov_b32_e32 v7, v0
	v_mov_b32_e32 v16, v0
	v_mov_b32_e32 v17, v0
	v_mov_b32_e32 v18, v0
	v_mov_b32_e32 v19, v0
	v_mov_b32_e32 v20, v0
	v_mov_b32_e32 v21, v0
	v_mov_b32_e32 v22, v0
	v_mov_b32_e32 v23, v0
	v_mov_b32_e32 v32, v0
	v_mov_b32_e32 v33, v0
	v_mov_b32_e32 v34, v0
	v_mov_b32_e32 v35, v0
	v_mov_b32_e32 v36, v0
	v_mov_b32_e32 v37, v0
	v_mov_b32_e32 v38, v0
	v_mov_b32_e32 v39, v0
	v_mov_b32_e32 v48, v0
	v_mov_b32_e32 v49, v0
	v_mov_b32_e32 v50, v0
	v_mov_b32_e32 v51, v0
	v_mov_b32_e32 v52, v0
	v_mov_b32_e32 v53, v0
	v_mov_b32_e32 v54, v0
	v_mov_b32_e32 v55, v0
	v_mov_b32_e32 v8, v0
	v_mov_b32_e32 v9, v0
	v_mov_b32_e32 v10, v0
	v_mov_b32_e32 v11, v0
	v_mov_b32_e32 v12, v0
	v_mov_b32_e32 v13, v0
	v_mov_b32_e32 v14, v0
	v_mov_b32_e32 v15, v0
	v_mov_b32_e32 v24, v0
	v_mov_b32_e32 v25, v0
	v_mov_b32_e32 v26, v0
	v_mov_b32_e32 v27, v0
	v_mov_b32_e32 v28, v0
	v_mov_b32_e32 v29, v0
	v_mov_b32_e32 v30, v0
	v_mov_b32_e32 v31, v0
	v_mov_b32_e32 v40, v0
	v_mov_b32_e32 v41, v0
	v_mov_b32_e32 v42, v0
	v_mov_b32_e32 v43, v0
	v_mov_b32_e32 v44, v0
	v_mov_b32_e32 v45, v0
	v_mov_b32_e32 v46, v0
	v_mov_b32_e32 v47, v0
	v_mov_b32_e32 v56, v0
	v_mov_b32_e32 v57, v0
	v_mov_b32_e32 v58, v0
	v_mov_b32_e32 v59, v0
	v_mov_b32_e32 v60, v0
	v_mov_b32_e32 v61, v0
	v_mov_b32_e32 v62, v0
	v_mov_b32_e32 v63, v0
	s_waitcnt vmcnt(0)
	v_mov_b32_e32 v64, v0
	v_mov_b32_e32 v65, v0
	v_mov_b32_e32 v66, v0
	v_mov_b32_e32 v67, v0
	v_mov_b32_e32 v68, v0
	v_mov_b32_e32 v69, v0
	v_mov_b32_e32 v70, v0
	v_mov_b32_e32 v71, v0
	v_mov_b32_e32 v80, v0
	v_mov_b32_e32 v81, v0
	v_mov_b32_e32 v82, v0
	v_mov_b32_e32 v83, v0
	v_mov_b32_e32 v84, v0
	v_mov_b32_e32 v85, v0
	v_mov_b32_e32 v86, v0
	v_mov_b32_e32 v87, v0
	v_mov_b32_e32 v96, v0
	v_mov_b32_e32 v97, v0
	v_mov_b32_e32 v98, v0
	v_mov_b32_e32 v99, v0
	v_mov_b32_e32 v100, v0
	v_mov_b32_e32 v101, v0
	v_mov_b32_e32 v102, v0
	v_mov_b32_e32 v103, v0
	v_mov_b32_e32 v128, v0
	v_mov_b32_e32 v129, v0
	v_mov_b32_e32 v130, v0
	v_mov_b32_e32 v131, v0
	v_mov_b32_e32 v132, v0
	v_mov_b32_e32 v133, v0
	v_mov_b32_e32 v134, v0
	v_mov_b32_e32 v135, v0
	v_mov_b32_e32 v72, v0
	v_mov_b32_e32 v73, v0
	v_mov_b32_e32 v74, v0
	v_mov_b32_e32 v75, v0
	v_mov_b32_e32 v76, v0
	v_mov_b32_e32 v77, v0
	v_mov_b32_e32 v78, v0
	v_mov_b32_e32 v79, v0
	v_mov_b32_e32 v88, v0
	v_mov_b32_e32 v89, v0
	v_mov_b32_e32 v90, v0
	v_mov_b32_e32 v91, v0
	v_mov_b32_e32 v92, v0
	v_mov_b32_e32 v93, v0
	v_mov_b32_e32 v94, v0
	v_mov_b32_e32 v95, v0
	v_mov_b32_e32 v104, v0
	v_mov_b32_e32 v105, v0
	v_mov_b32_e32 v106, v0
	v_mov_b32_e32 v107, v0
	v_mov_b32_e32 v108, v0
	v_mov_b32_e32 v109, v0
	v_mov_b32_e32 v110, v0
	v_mov_b32_e32 v111, v0
	v_mov_b32_e32 v136, v0
	v_mov_b32_e32 v137, v0
	v_mov_b32_e32 v138, v0
	v_mov_b32_e32 v139, v0
	v_mov_b32_e32 v140, v0
	v_mov_b32_e32 v141, v0
	v_mov_b32_e32 v142, v0
	v_mov_b32_e32 v143, v0
	s_branch .LBB0_205
	s_nop 0
	s_nop 0
	s_nop 0

; #define WAIT_BAR(N) asm volatile("s_waitcnt vmcnt(" #N ") lgkmcnt(0)\n\ts_barrier":::"memory")
;   #define DMA_K(t,slot) glds16(ksrc+(long)(t)*KVBLK*kp,(unsigned)__builtin_amdgcn_readfirstlane(kdst+(slot)))
;   #define DMA_V(t,slot) glds16(vsrc+(long)(t)*KVBLK*kp,(unsigned)__builtin_amdgcn_readfirstlane(vdst+(slot)))
;   #define CMASK(P0,P1,t) NAMASK(P0,P1,t)
;   #define ROT() do{sl_prev=sl_cur;sl_cur=sl_next;sl_next=(sl_next==(NSLOT-1)*SLOTB)?0:sl_next+SLOTB;}while(0)
; template<int THRL,bool NA> __device__ __forceinline__ int attn_unit(const bf16*Qu,bf16*Ou,int qp,const bf16*__restrict__ Kh,const bf16*__restrict__ Vh,int kp,int NT,char*shm, ...
;     ...
;   if(!pre){DMA_K(2,s2b);}
;   WAIT_BAR(3);
;   if constexpr(NA||THRL<0){const f32x16 z_=f32x16{};qkt(pA0,pA1,Kbase+s0b,qr,z_,r32,hi);}else{qkt(pA0,pA1,Kbase+s0b,qr,negm,r32,hi);}asm volatile("s_nop 15\n\ts_nop 7":"+v"(pA0),"+v"(pA1));CMASK(pA0,pA1,0);
;   START(pA0,pA1);
;   _Pragma("unroll") for(int r=0;r<16;++r)pA1[r]=__builtin_amdgcn_exp2f(pA1[r]);
;   WAIT_BAR(0);
;   DMA_K(3,s0b);DMA_V(1,s1b);
;   ROT();
;   kload8(kf,kp0+sl_cur);
;   WAIT_BAR(2);
.LBB0_389:
	v_lshlrev_b32_e32 v44, 10, v184
	v_lshlrev_b32_e32 v45, 4, v183
	s_add_i32 s0, s94, 0
	s_waitcnt vmcnt(3) lgkmcnt(0)
	s_barrier
	v_add3_u32 v40, s0, v44, v45
	ds_read_b128 v[2:5], v40
	ds_read_b128 v[36:39], v40 offset:2048
	v_lshlrev_b32_e32 v175, 8, v35
	v_lshlrev_b32_e32 v35, 1, v34
	v_lshlrev_b32_e32 v34, 4, v34
	v_and_b32_e32 v187, 32, v35
	s_waitcnt vmcnt(3) lgkmcnt(1)
	v_mfma_f32_32x32x16_bf16 v[18:33], v[2:5], v[126:129], 0
	ds_read_b128 v[2:5], v40 offset:512
	v_and_b32_e32 v34, 0xc0, v34
	v_lshl_or_b32 v186, v184, 8, v34
	v_add_u32_e32 v34, 0, v187
	v_add3_u32 v190, v34, v185, v186
	v_lshl_add_u64 v[34:35], v[176:177], 0, s[46:47]
	v_add3_u32 v191, 0, v44, v45
	s_waitcnt vmcnt(2) lgkmcnt(1)
	v_mfma_f32_32x32x16_bf16 v[18:33], v[36:39], v[118:121], v[18:33]
	ds_read_b128 v[36:39], v40 offset:2560
	s_add_i32 s0, s13, s94
	v_mov_b32_e32 v189, 0
	v_lshlrev_b32_e32 v188, 8, v1
	s_mov_b32 s76, 1
	s_add_i32 s2, s93, -5
	v_lshl_add_u64 v[162:163], v[178:179], 0, s[46:47]
	s_waitcnt lgkmcnt(1)
	v_mfma_f32_32x32x16_bf16 v[2:17], v[2:5], v[126:129], 0
	v_lshl_add_u64 v[164:165], v[176:177], 0, s[50:51]
	v_lshl_add_u64 v[66:67], v[178:179], 0, s[60:61]
	s_mov_b32 s8, 5
	s_waitcnt lgkmcnt(0)
	v_mfma_f32_32x32x16_bf16 v[2:17], v[36:39], v[118:121], v[2:17]
	ds_read_b128 v[36:39], v40 offset:4096
	s_waitcnt vmcnt(1) lgkmcnt(0)
	v_mfma_f32_32x32x16_bf16 v[18:33], v[36:39], v[110:113], v[18:33]
	ds_read_b128 v[36:39], v40 offset:4608
	s_waitcnt lgkmcnt(0)
	v_mfma_f32_32x32x16_bf16 v[2:17], v[36:39], v[110:113], v[2:17]
	ds_read_b128 v[36:39], v40 offset:6144
	ds_read_b128 v[40:43], v40 offset:6656
	s_waitcnt vmcnt(0) lgkmcnt(1)
	v_mfma_f32_32x32x16_bf16 v[18:33], v[36:39], v[102:105], v[18:33]
	s_waitcnt lgkmcnt(0)
	v_mfma_f32_32x32x16_bf16 v[2:17], v[40:43], v[102:105], v[2:17]
	s_nop 15
	s_nop 7
	s_waitcnt vmcnt(0) lgkmcnt(0)
	s_barrier
	s_mov_b32 s1, m0
	s_mov_b32 m0, s0
	s_nop 0
	global_load_lds_dwordx4 v[34:35], off
	s_mov_b32 m0, s1
	v_lshl_add_u64 v[34:35], v[178:179], 0, s[40:41]
	s_add_i32 s0, s34, s35
	s_mov_b32 s1, m0
	s_mov_b32 m0, s0
	s_nop 0
	global_load_lds_dwordx4 v[34:35], off
	s_mov_b32 m0, s1
	v_add_u32_e32 v34, s35, v191
	ds_read_b128 v[158:161], v34
	ds_read_b128 v[154:157], v34 offset:512
	ds_read_b128 v[150:153], v34 offset:2048
	ds_read_b128 v[146:149], v34 offset:2560
	ds_read_b128 v[142:145], v34 offset:4096
	ds_read_b128 v[138:141], v34 offset:4608
	ds_read_b128 v[134:137], v34 offset:6144
	ds_read_b128 v[130:133], v34 offset:6656
	v_exp_f32_e32 v50, v18
	v_exp_f32_e32 v51, v19
	v_exp_f32_e32 v52, v20
	v_exp_f32_e32 v53, v21
	v_exp_f32_e32 v54, v22
	v_exp_f32_e32 v55, v23
	v_exp_f32_e32 v56, v24
	v_exp_f32_e32 v57, v25
	v_exp_f32_e32 v58, v26
	v_exp_f32_e32 v59, v27
	v_exp_f32_e32 v60, v28
	v_exp_f32_e32 v61, v29
	v_exp_f32_e32 v62, v30
	v_exp_f32_e32 v63, v31
	v_exp_f32_e32 v64, v32
	v_exp_f32_e32 v65, v33
	v_exp_f32_e32 v34, v2
	v_exp_f32_e32 v35, v3
	v_exp_f32_e32 v36, v4
	v_exp_f32_e32 v37, v5
	v_exp_f32_e32 v38, v6
	v_exp_f32_e32 v39, v7
	v_exp_f32_e32 v40, v8
	v_exp_f32_e32 v41, v9
	v_exp_f32_e32 v42, v10
	v_exp_f32_e32 v43, v11
	v_exp_f32_e32 v44, v12
	v_exp_f32_e32 v45, v13
	v_exp_f32_e32 v46, v14
	v_exp_f32_e32 v47, v15
	v_exp_f32_e32 v48, v16
	v_exp_f32_e32 v49, v17
	s_waitcnt vmcnt(2) lgkmcnt(0)
	s_barrier
	v_mov_b32_e32 v2, 0
	v_mov_b32_e32 v3, v189
	v_mov_b32_e32 v4, v189
	v_mov_b32_e32 v5, v189
	v_mov_b32_e32 v6, v189
	v_mov_b32_e32 v7, v189
	v_mov_b32_e32 v8, v189
	v_mov_b32_e32 v9, v189
	v_mov_b32_e32 v10, v189
	v_mov_b32_e32 v11, v189
	v_mov_b32_e32 v12, v189
	v_mov_b32_e32 v13, v189
	v_mov_b32_e32 v14, v189
	v_mov_b32_e32 v15, v189
	v_mov_b32_e32 v16, v189
	v_mov_b32_e32 v17, v189
	v_mov_b32_e32 v18, 0
	v_mov_b32_e32 v19, v189
	v_mov_b32_e32 v20, v189
	v_mov_b32_e32 v21, v189
	v_mov_b32_e32 v22, v189
	v_mov_b32_e32 v23, v189
	v_mov_b32_e32 v24, v189
	v_mov_b32_e32 v25, v189
	v_mov_b32_e32 v26, v189
	v_mov_b32_e32 v27, v189
	v_mov_b32_e32 v28, v189
	v_mov_b32_e32 v29, v189
	v_mov_b32_e32 v30, v189
	v_mov_b32_e32 v31, v189
	v_mov_b32_e32 v32, v189
	v_mov_b32_e32 v33, v189
	s_nop 0
	s_nop 0
.LBB0_390:
	s_mov_b32 s1, s9
	v_mov_b64_e32 v[180:181], v[66:67]
	s_mov_b32 s0, s8
	s_mov_b32 s3, s35
	v_add_u32_e32 v166, s94, v190
	ds_read_b64_tr_b16 v[168:169], v166 offset:24576
	ds_read_b64_tr_b16 v[170:171], v166 offset:25088
	v_add_f32_e32 v66, v50, v51
	v_add_f32_e32 v66, v52, v66
	v_add_f32_e32 v66, v53, v66
	v_add_f32_e32 v66, v54, v66
	v_add_f32_e32 v66, v55, v66
	v_cvt_pk_bf16_f32 v122, v50, v51
	v_cvt_pk_bf16_f32 v123, v52, v53
	s_waitcnt lgkmcnt(9)
	v_mfma_f32_32x32x16_bf16 v[82:97], v[158:161], v[126:129], 0
	ds_read_b64_tr_b16 v[50:51], v166 offset:28672
	ds_read_b64_tr_b16 v[52:53], v166 offset:29184
	v_add_f32_e32 v66, v56, v66
	v_add_f32_e32 v66, v57, v66
	v_add_f32_e32 v66, v58, v66
	v_add_f32_e32 v98, v59, v66
	s_waitcnt lgkmcnt(10)
	v_mfma_f32_32x32x16_bf16 v[66:81], v[154:157], v[126:129], 0
	v_cvt_pk_bf16_f32 v124, v54, v55
	v_cvt_pk_bf16_f32 v125, v56, v57
	ds_read_b64_tr_b16 v[54:55], v166 offset:25600
	ds_read_b64_tr_b16 v[56:57], v166 offset:26112
	v_add_f32_e32 v98, v60, v98
	v_add_f32_e32 v98, v61, v98
	v_add_f32_e32 v98, v62, v98
	v_add_f32_e32 v98, v63, v98
	v_cvt_pk_bf16_f32 v114, v58, v59
	v_cvt_pk_bf16_f32 v115, v60, v61
	s_waitcnt lgkmcnt(11)
	v_mfma_f32_32x32x16_bf16 v[82:97], v[150:153], v[118:121], v[82:97]
	ds_read_b64_tr_b16 v[58:59], v166 offset:29696
	ds_read_b64_tr_b16 v[60:61], v166 offset:30208
	s_waitcnt lgkmcnt(12)
; #define WAIT_BAR(N) asm volatile("s_waitcnt vmcnt(" #N ") lgkmcnt(0)\n\ts_barrier":::"memory")
;   #define RESC() do{ if(resc){ asm volatile("s_waitcnt lgkmcnt(0)":::"memory"); \
;       _Pragma("unroll") for(int d_=0;d_<2;++d_) _Pragma("unroll") for(int r=0;r<16;++r)o[d_][r]*=wsf[crow(r,hi)]; } }while(0)
;   #define ROT() do{sl_prev=sl_cur;sl_cur=sl_next;sl_next=(sl_next==(NSLOT-1)*SLOTB)?0:sl_next+SLOTB;}while(0)
; template<int THRL,bool NA> __device__ __forceinline__ int attn_unit(const bf16*Qu,bf16*Ou,int qp,const bf16*__restrict__ Kh,const bf16*__restrict__ Vh,int kp,int NT,char*shm, ...
;     ...
;   int t=1;
;   for(;t+5<NT;t+=2){
;     STEP(pB0,pB1,pA0,pA1,t,true,true,true);     WAIT_BAR(2); RESC(); ROT();
	v_mfma_f32_32x32x16_bf16 v[66:81], v[146:149], v[118:121], v[66:81]
	v_add_f32_e32 v98, v64, v98
	v_add_f32_e32 v98, v65, v98
	v_add_f32_e32 v98, v34, v98
	v_add_f32_e32 v98, v35, v98
	v_cvt_pk_bf16_f32 v116, v62, v63
	v_cvt_pk_bf16_f32 v117, v64, v65
	ds_read_b64_tr_b16 v[62:63], v166 offset:26624
	ds_read_b64_tr_b16 v[64:65], v166 offset:27136
	v_add_f32_e32 v98, v36, v98
	v_add_f32_e32 v98, v37, v98
	v_add_f32_e32 v98, v38, v98
	v_add_f32_e32 v98, v39, v98
	v_cvt_pk_bf16_f32 v106, v34, v35
	v_cvt_pk_bf16_f32 v107, v36, v37
	s_waitcnt lgkmcnt(13)
	v_mfma_f32_32x32x16_bf16 v[82:97], v[142:145], v[110:113], v[82:97]
	ds_read_b64_tr_b16 v[34:35], v166 offset:30720
	ds_read_b64_tr_b16 v[36:37], v166 offset:31232
	s_waitcnt lgkmcnt(14)
	v_mfma_f32_32x32x16_bf16 v[66:81], v[138:141], v[110:113], v[66:81]
	v_add_f32_e32 v98, v40, v98
	v_add_f32_e32 v98, v41, v98
	v_add_f32_e32 v98, v42, v98
	v_add_f32_e32 v98, v43, v98
	v_cvt_pk_bf16_f32 v108, v38, v39
	v_cvt_pk_bf16_f32 v109, v40, v41
	ds_read_b64_tr_b16 v[38:39], v166 offset:27648
	ds_read_b64_tr_b16 v[40:41], v166 offset:28160
	v_add_f32_e32 v98, v44, v98
	v_add_f32_e32 v98, v45, v98
	v_add_f32_e32 v98, v46, v98
	v_add_f32_e32 v138, v47, v98
	v_cvt_pk_bf16_f32 v98, v42, v43
	v_cvt_pk_bf16_f32 v99, v44, v45
	s_waitcnt lgkmcnt(14)
	v_mfma_f32_32x32x16_bf16 v[82:97], v[134:137], v[102:105], v[82:97]
	ds_read_b64_tr_b16 v[42:43], v166 offset:31744
	ds_read_b64_tr_b16 v[44:45], v166 offset:32256
	v_mfma_f32_32x32x16_bf16 v[66:81], v[130:133], v[102:105], v[66:81]
	v_add_f32_e32 v100, v48, v138
	v_add_f32_e32 v100, v49, v100
	v_add_f32_e32 v166, 0, v100
	v_cvt_pk_bf16_f32 v100, v46, v47
	v_cvt_pk_bf16_f32 v101, v48, v49
	v_lshl_add_u64 v[46:47], v[164:165], 0, s[62:63]
	s_add_i32 s8, s35, s13
	s_mov_b32 s9, m0
	s_mov_b32 m0, s8
	s_nop 0
	global_load_lds_dwordx4 v[46:47], off
	s_mov_b32 m0, s9
	v_lshl_add_u64 v[46:47], v[162:163], 0, s[62:63]
	s_add_i32 s8, s1, s34
	s_mov_b32 s9, m0
	s_mov_b32 m0, s8
	s_nop 0
	global_load_lds_dwordx4 v[46:47], off
	s_mov_b32 m0, s9
	s_waitcnt lgkmcnt(14)
	v_mfma_f32_32x32x16_bf16 v[2:17], v[122:125], v[168:171], v[2:17]
	v_exp_f32_e32 v82, v82
	v_exp_f32_e32 v83, v83
	v_exp_f32_e32 v84, v84
	v_exp_f32_e32 v85, v85
	s_waitcnt lgkmcnt(12)
	v_mfma_f32_32x32x16_bf16 v[18:33], v[122:125], v[50:53], v[18:33]
	v_exp_f32_e32 v86, v86
	v_exp_f32_e32 v87, v87
	v_exp_f32_e32 v88, v88
	v_exp_f32_e32 v89, v89
	v_add_u32_e32 v50, s1, v191
	ds_read_b128 v[46:49], v50
	ds_read_b128 v[130:133], v50 offset:512
	s_waitcnt lgkmcnt(12)
	v_mfma_f32_32x32x16_bf16 v[2:17], v[114:117], v[54:57], v[2:17]
	v_exp_f32_e32 v90, v90
	v_exp_f32_e32 v91, v91
	v_exp_f32_e32 v92, v92
	v_exp_f32_e32 v93, v93
	ds_read_b128 v[134:137], v50 offset:2048
	ds_read_b128 v[138:141], v50 offset:2560
	s_waitcnt lgkmcnt(12)
	v_mfma_f32_32x32x16_bf16 v[18:33], v[114:117], v[58:61], v[18:33]
	v_exp_f32_e32 v94, v94
	v_exp_f32_e32 v95, v95
	v_exp_f32_e32 v96, v96
	v_exp_f32_e32 v97, v97
	ds_read_b128 v[142:145], v50 offset:4096
	ds_read_b128 v[146:149], v50 offset:4608
	s_waitcnt lgkmcnt(12)
	v_mfma_f32_32x32x16_bf16 v[2:17], v[106:109], v[62:65], v[2:17]
	v_exp_f32_e32 v66, v66
	v_exp_f32_e32 v67, v67
	v_exp_f32_e32 v68, v68
	v_exp_f32_e32 v69, v69
	ds_read_b128 v[150:153], v50 offset:6144
	ds_read_b128 v[154:157], v50 offset:6656
	s_waitcnt lgkmcnt(12)
	v_mfma_f32_32x32x16_bf16 v[18:33], v[106:109], v[34:37], v[18:33]
	v_exp_f32_e32 v70, v70
	v_exp_f32_e32 v71, v71
	v_exp_f32_e32 v72, v72
	v_exp_f32_e32 v73, v73
	s_waitcnt lgkmcnt(10)
	v_mfma_f32_32x32x16_bf16 v[2:17], v[98:101], v[38:41], v[2:17]
	v_exp_f32_e32 v74, v74
	v_exp_f32_e32 v75, v75
	v_exp_f32_e32 v76, v76
	v_exp_f32_e32 v77, v77
	s_waitcnt lgkmcnt(8)
	v_mfma_f32_32x32x16_bf16 v[18:33], v[98:101], v[42:45], v[18:33]
	v_exp_f32_e32 v78, v78
	v_exp_f32_e32 v79, v79
	v_exp_f32_e32 v80, v80
	v_exp_f32_e32 v81, v81
	s_waitcnt vmcnt(2) lgkmcnt(0)
	s_barrier
; #define WAIT_BAR(N) asm volatile("s_waitcnt vmcnt(" #N ") lgkmcnt(0)\n\ts_barrier":::"memory")
;   #define RESC() do{ if(resc){ asm volatile("s_waitcnt lgkmcnt(0)":::"memory"); \
;       _Pragma("unroll") for(int d_=0;d_<2;++d_) _Pragma("unroll") for(int r=0;r<16;++r)o[d_][r]*=wsf[crow(r,hi)]; } }while(0)
;   #define ROT() do{sl_prev=sl_cur;sl_cur=sl_next;sl_next=(sl_next==(NSLOT-1)*SLOTB)?0:sl_next+SLOTB;}while(0)
;   #define ENDW(tt) do{ if((tt)+3<NT){WAIT_BAR(2);} else if((tt)+2<NT){WAIT_BAR(1);} else {WAIT_BAR(0);} }while(0)
; template<int THRL,bool NA> __device__ __forceinline__ int attn_unit(const bf16*Qu,bf16*Ou,int qp,const bf16*__restrict__ Kh,const bf16*__restrict__ Vh,int kp,int NT,char*shm, ...
;     ...
;   int t=1;
;   for(;t+5<NT;t+=2){
;     STEP(pB0,pB1,pA0,pA1,t,true,true,true);     WAIT_BAR(2); RESC(); ROT();
;     STEP(pA0,pA1,pB0,pB1,t+1,true,true,true);   WAIT_BAR(2); RESC(); ROT();
;   }
;     ...
;   for(;t+1<NT;t+=2){
;     STEP(pB0,pB1,pA0,pA1,t,(t+3<NT),(t+1<NT),(t+1<NT));       ENDW(t);   RESC(); ROT();
	s_add_i32 s8, s1, 0x2000
	s_cmpk_lg_i32 s1, 0x4000
	s_cselect_b32 s35, s8, 0
	v_add_u32_e32 v167, s3, v190
	ds_read_b64_tr_b16 v[158:159], v167 offset:24576
	ds_read_b64_tr_b16 v[160:161], v167 offset:25088
	s_waitcnt lgkmcnt(9)
	v_mfma_f32_32x32x16_bf16 v[50:65], v[46:49], v[126:129], 0
	v_add_f32_e32 v34, v82, v83
	v_add_f32_e32 v34, v84, v34
	v_add_f32_e32 v34, v85, v34
	v_add_f32_e32 v34, v86, v34
	v_add_f32_e32 v34, v87, v34
	v_cvt_pk_bf16_f32 v122, v82, v83
	v_cvt_pk_bf16_f32 v123, v84, v85
	ds_read_b64_tr_b16 v[82:83], v167 offset:28672
	ds_read_b64_tr_b16 v[84:85], v167 offset:29184
	v_add_f32_e32 v34, v88, v34
	v_add_f32_e32 v34, v89, v34
	v_add_f32_e32 v34, v90, v34
	v_add_f32_e32 v98, v91, v34
	s_waitcnt lgkmcnt(10)
	v_mfma_f32_32x32x16_bf16 v[34:49], v[130:133], v[126:129], 0
	v_cvt_pk_bf16_f32 v124, v86, v87
	v_cvt_pk_bf16_f32 v125, v88, v89
	ds_read_b64_tr_b16 v[86:87], v167 offset:25600
	ds_read_b64_tr_b16 v[88:89], v167 offset:26112
	s_waitcnt lgkmcnt(11)
	v_mfma_f32_32x32x16_bf16 v[50:65], v[134:137], v[118:121], v[50:65]
	v_add_f32_e32 v98, v92, v98
	v_add_f32_e32 v98, v93, v98
	v_add_f32_e32 v98, v94, v98
	v_add_f32_e32 v98, v95, v98
	v_cvt_pk_bf16_f32 v114, v90, v91
	v_cvt_pk_bf16_f32 v115, v92, v93
	ds_read_b64_tr_b16 v[90:91], v167 offset:29696
	ds_read_b64_tr_b16 v[92:93], v167 offset:30208
	s_waitcnt lgkmcnt(12)
	v_mfma_f32_32x32x16_bf16 v[34:49], v[138:141], v[118:121], v[34:49]
	v_add_f32_e32 v98, v96, v98
	v_add_f32_e32 v98, v97, v98
	v_add_f32_e32 v98, v66, v98
	v_add_f32_e32 v98, v67, v98
	v_cvt_pk_bf16_f32 v116, v94, v95
	v_cvt_pk_bf16_f32 v117, v96, v97
	ds_read_b64_tr_b16 v[94:95], v167 offset:26624
	ds_read_b64_tr_b16 v[96:97], v167 offset:27136
	s_waitcnt lgkmcnt(13)
	v_mfma_f32_32x32x16_bf16 v[50:65], v[142:145], v[110:113], v[50:65]
	v_add_f32_e32 v98, v68, v98
	v_add_f32_e32 v98, v69, v98
	v_add_f32_e32 v98, v70, v98
	v_add_f32_e32 v98, v71, v98
	v_cvt_pk_bf16_f32 v106, v66, v67
	v_cvt_pk_bf16_f32 v107, v68, v69
	ds_read_b64_tr_b16 v[66:67], v167 offset:30720
	ds_read_b64_tr_b16 v[68:69], v167 offset:31232
	s_waitcnt lgkmcnt(14)
	v_mfma_f32_32x32x16_bf16 v[34:49], v[146:149], v[110:113], v[34:49]
	v_add_f32_e32 v98, v72, v98
	v_add_f32_e32 v98, v73, v98
	v_add_f32_e32 v98, v74, v98
	v_add_f32_e32 v98, v75, v98
	v_cvt_pk_bf16_f32 v108, v70, v71
	v_cvt_pk_bf16_f32 v109, v72, v73
	ds_read_b64_tr_b16 v[70:71], v167 offset:27648
	ds_read_b64_tr_b16 v[72:73], v167 offset:28160
	s_waitcnt lgkmcnt(14)
	v_mfma_f32_32x32x16_bf16 v[50:65], v[150:153], v[102:105], v[50:65]
	v_add_f32_e32 v98, v76, v98
	v_add_f32_e32 v98, v77, v98
	v_add_f32_e32 v98, v78, v98
	v_add_f32_e32 v130, v79, v98
	v_cvt_pk_bf16_f32 v98, v74, v75
	v_cvt_pk_bf16_f32 v99, v76, v77
	ds_read_b64_tr_b16 v[74:75], v167 offset:31744
	ds_read_b64_tr_b16 v[76:77], v167 offset:32256
	v_mfma_f32_32x32x16_bf16 v[34:49], v[154:157], v[102:105], v[34:49]
	v_add_f32_e32 v100, v80, v130
	v_add_f32_e32 v100, v81, v100
	v_add_f32_e32 v167, 0, v100
	v_cvt_pk_bf16_f32 v100, v78, v79
	v_cvt_pk_bf16_f32 v101, v80, v81
	s_add_i32 s3, s1, s13
	s_mov_b32 s8, m0
	s_mov_b32 m0, s3
	s_nop 0
	global_load_lds_dwordx4 v[164:165], off
	s_mov_b32 m0, s8
	s_add_i32 s3, s35, s34
	s_mov_b32 s8, m0
	s_mov_b32 m0, s3
	s_nop 0
	global_load_lds_dwordx4 v[162:163], off
	s_mov_b32 m0, s8
	s_add_i32 s76, s76, 2
	s_waitcnt lgkmcnt(14)
	v_mfma_f32_32x32x16_bf16 v[2:17], v[122:125], v[158:161], v[2:17]
	v_exp_f32_e32 v50, v50
	v_exp_f32_e32 v51, v51
	v_exp_f32_e32 v52, v52
	v_exp_f32_e32 v53, v53
	s_waitcnt lgkmcnt(12)
	v_mfma_f32_32x32x16_bf16 v[18:33], v[122:125], v[82:85], v[18:33]
	v_exp_f32_e32 v54, v54
	v_exp_f32_e32 v55, v55
	v_exp_f32_e32 v56, v56
	v_exp_f32_e32 v57, v57
	v_add_u32_e32 v78, s35, v191
	ds_read_b128 v[158:161], v78
	ds_read_b128 v[154:157], v78 offset:512
	s_waitcnt lgkmcnt(12)
	v_mfma_f32_32x32x16_bf16 v[2:17], v[114:117], v[86:89], v[2:17]
	v_exp_f32_e32 v58, v58
	v_exp_f32_e32 v59, v59
	v_exp_f32_e32 v60, v60
	v_exp_f32_e32 v61, v61
	ds_read_b128 v[150:153], v78 offset:2048
	ds_read_b128 v[146:149], v78 offset:2560
	s_waitcnt lgkmcnt(12)
	v_mfma_f32_32x32x16_bf16 v[18:33], v[114:117], v[90:93], v[18:33]
	v_exp_f32_e32 v62, v62
	v_exp_f32_e32 v63, v63
	v_exp_f32_e32 v64, v64
	v_exp_f32_e32 v65, v65
	ds_read_b128 v[142:145], v78 offset:4096
	ds_read_b128 v[138:141], v78 offset:4608
	s_waitcnt lgkmcnt(12)
	v_mfma_f32_32x32x16_bf16 v[2:17], v[106:109], v[94:97], v[2:17]
	v_exp_f32_e32 v34, v34
	v_exp_f32_e32 v35, v35
	v_exp_f32_e32 v36, v36
	v_exp_f32_e32 v37, v37
	ds_read_b128 v[134:137], v78 offset:6144
	ds_read_b128 v[130:133], v78 offset:6656
	s_waitcnt lgkmcnt(12)
	v_mfma_f32_32x32x16_bf16 v[18:33], v[106:109], v[66:69], v[18:33]
	v_exp_f32_e32 v38, v38
	v_exp_f32_e32 v39, v39
	v_exp_f32_e32 v40, v40
	v_exp_f32_e32 v41, v41
	s_waitcnt lgkmcnt(10)
	v_mfma_f32_32x32x16_bf16 v[2:17], v[98:101], v[70:73], v[2:17]
	v_exp_f32_e32 v42, v42
	v_exp_f32_e32 v43, v43
	v_exp_f32_e32 v44, v44
	v_exp_f32_e32 v45, v45
	s_waitcnt lgkmcnt(8)
	v_mfma_f32_32x32x16_bf16 v[18:33], v[98:101], v[74:77], v[18:33]
	v_exp_f32_e32 v46, v46
	v_exp_f32_e32 v47, v47
	v_exp_f32_e32 v48, v48
	v_exp_f32_e32 v49, v49
	s_add_i32 s3, s35, 0x2000
	s_waitcnt vmcnt(2) lgkmcnt(0)
	s_barrier
	s_cmpk_lg_i32 s35, 0x4000
	v_add_f32_e32 v68, v189, v166
	s_cselect_b32 s9, s3, 0
	s_add_i32 s8, s0, 2
	v_lshl_add_u64 v[162:163], v[162:163], 0, s[44:45]
	v_lshl_add_u64 v[164:165], v[164:165], 0, s[44:45]
	v_lshl_add_u64 v[66:67], v[180:181], 0, s[44:45]
	s_mov_b32 s94, s1
	s_cmp_ge_u32 s76, s2
	v_add_f32_e32 v189, v68, v167
	s_cbranch_scc0 .LBB0_390
	s_add_i32 s2, s76, 1
	s_cmp_ge_u32 s2, s93
	s_cbranch_scc1 .LBB0_425
	s_add_i32 s77, s93, -2
	s_nop 0
	s_nop 0
	s_nop 0
	s_nop 0
	s_nop 0
	s_nop 0
	s_nop 0
	s_nop 0
	s_nop 0
	s_nop 0
	s_nop 0
	s_nop 0
	s_nop 0

; template <class Epi, class Sched, bool ALIGN_EPI = false, bool SP2 = false>
; __device__ __forceinline__ void gemm_phase(PG8_LAS unsigned char* lds, const Gemm g, const Sched& S, const Epi& E, const int wave_s) {
;     ...
;         const bool has_next = S.next(ui + 1, nxt);
;         const char* nA = has_next ? (const char*)g.A + (size_t)nxt.pm * tA : cA; const char* nB = has_next ? (const char*)g.Bt + (size_t)nxt.pn * tB : cB;
;     ...
; #pragma unroll
;         for (int a = 0; a < 2; ++a)
; #pragma unroll
;             for (int b = 0; b < 2; ++b)
; #pragma unroll
;                 for (int m = 0; m < 4; ++m)
; #pragma unroll
;                     for (int n = 0; n < 2; ++n) acc[a][b][m][n] = (f32x4){0.f, 0.f, 0.f, 0.f};
;         cur = nxt; cA = nA; cB = nB; ++ui;
.LBB0_621:
	s_ashr_i32 s51, s50, 31
	s_lshl_b64 s[34:35], s[50:51], 19
	s_add_u32 s60, s14, s34
	s_addc_u32 s61, s15, s35
	s_and_b64 s[34:35], s[2:3], exec
	s_cselect_b32 s34, s61, s65
	s_cselect_b32 s35, s60, s64
	s_ashr_i32 s49, s48, 31
	s_lshl_b64 s[62:63], s[48:49], 19
	s_add_u32 s62, s58, s62
	s_addc_u32 s63, s59, s63
	s_and_b64 s[70:71], s[2:3], exec
	s_cselect_b32 s90, s63, s69
	s_cselect_b32 s91, s62, s68
	s_lshl_b32 s51, s66, 8
	s_lshl_b32 s8, s8, 8
	s_or_b32 s49, s8, s11
	s_add_i32 s51, s51, s80
	s_add_u32 s92, s68, 0x100
	v_mov_b32_e32 v0, 0
	v_lshl_add_u64 v[148:149], s[64:65], 0, v[140:141]
	v_lshl_add_u64 v[150:151], s[64:65], 0, v[142:143]
	s_addc_u32 s93, s69, 0
	s_mov_b32 s94, -2
	s_mov_b64 s[66:67], 0
	v_mov_b32_e32 v1, v0
	v_mov_b32_e32 v2, v0
	v_mov_b32_e32 v3, v0
	v_mov_b32_e32 v4, v0
	v_mov_b32_e32 v5, v0
	v_mov_b32_e32 v6, v0
	v_mov_b32_e32 v7, v0
	v_mov_b32_e32 v16, v0
	v_mov_b32_e32 v17, v0
	v_mov_b32_e32 v18, v0
	v_mov_b32_e32 v19, v0
	v_mov_b32_e32 v20, v0
	v_mov_b32_e32 v21, v0
	v_mov_b32_e32 v22, v0
	v_mov_b32_e32 v23, v0
	v_mov_b32_e32 v32, v0
	v_mov_b32_e32 v33, v0
	v_mov_b32_e32 v34, v0
	v_mov_b32_e32 v35, v0
	v_mov_b32_e32 v36, v0
	v_mov_b32_e32 v37, v0
	v_mov_b32_e32 v38, v0
	v_mov_b32_e32 v39, v0
	v_mov_b32_e32 v48, v0
	v_mov_b32_e32 v49, v0
	v_mov_b32_e32 v50, v0
	v_mov_b32_e32 v51, v0
	v_mov_b32_e32 v52, v0
	v_mov_b32_e32 v53, v0
	v_mov_b32_e32 v54, v0
	v_mov_b32_e32 v55, v0
	v_mov_b32_e32 v8, v0
	v_mov_b32_e32 v9, v0
	v_mov_b32_e32 v10, v0
	v_mov_b32_e32 v11, v0
	v_mov_b32_e32 v12, v0
	v_mov_b32_e32 v13, v0
	v_mov_b32_e32 v14, v0
	v_mov_b32_e32 v15, v0
	v_mov_b32_e32 v24, v0
	v_mov_b32_e32 v25, v0
	v_mov_b32_e32 v26, v0
	v_mov_b32_e32 v27, v0
	v_mov_b32_e32 v28, v0
	v_mov_b32_e32 v29, v0
	v_mov_b32_e32 v30, v0
	v_mov_b32_e32 v31, v0
	v_mov_b32_e32 v40, v0
	v_mov_b32_e32 v41, v0
	v_mov_b32_e32 v42, v0
	v_mov_b32_e32 v43, v0
	v_mov_b32_e32 v44, v0
	v_mov_b32_e32 v45, v0
	v_mov_b32_e32 v46, v0
	v_mov_b32_e32 v47, v0
	v_mov_b32_e32 v56, v0
	v_mov_b32_e32 v57, v0
	v_mov_b32_e32 v58, v0
	v_mov_b32_e32 v59, v0
	v_mov_b32_e32 v60, v0
	v_mov_b32_e32 v61, v0
	v_mov_b32_e32 v62, v0
	v_mov_b32_e32 v63, v0
	v_mov_b32_e32 v64, v0
	v_mov_b32_e32 v65, v0
	v_mov_b32_e32 v66, v0
	v_mov_b32_e32 v67, v0
	v_mov_b32_e32 v68, v0
	v_mov_b32_e32 v69, v0
	v_mov_b32_e32 v70, v0
	v_mov_b32_e32 v71, v0
	v_mov_b32_e32 v80, v0
	v_mov_b32_e32 v81, v0
	v_mov_b32_e32 v82, v0
	v_mov_b32_e32 v83, v0
	v_mov_b32_e32 v84, v0
	v_mov_b32_e32 v85, v0
	v_mov_b32_e32 v86, v0
	v_mov_b32_e32 v87, v0
	v_mov_b32_e32 v96, v0
	v_mov_b32_e32 v97, v0
	v_mov_b32_e32 v98, v0
	v_mov_b32_e32 v99, v0
	v_mov_b32_e32 v100, v0
	v_mov_b32_e32 v101, v0
	v_mov_b32_e32 v102, v0
	v_mov_b32_e32 v103, v0
	v_mov_b32_e32 v112, v0
	v_mov_b32_e32 v113, v0
	v_mov_b32_e32 v114, v0
	v_mov_b32_e32 v115, v0
	v_mov_b32_e32 v116, v0
	v_mov_b32_e32 v117, v0
	v_mov_b32_e32 v118, v0
	v_mov_b32_e32 v119, v0
	v_mov_b32_e32 v72, v0
	v_mov_b32_e32 v73, v0
	v_mov_b32_e32 v74, v0
	v_mov_b32_e32 v75, v0
	v_mov_b32_e32 v76, v0
	v_mov_b32_e32 v77, v0
	v_mov_b32_e32 v78, v0
	v_mov_b32_e32 v79, v0
	v_mov_b32_e32 v88, v0
	v_mov_b32_e32 v89, v0
	v_mov_b32_e32 v90, v0
	v_mov_b32_e32 v91, v0
	v_mov_b32_e32 v92, v0
	v_mov_b32_e32 v93, v0
	v_mov_b32_e32 v94, v0
	v_mov_b32_e32 v95, v0
	v_mov_b32_e32 v104, v0
	v_mov_b32_e32 v105, v0
	v_mov_b32_e32 v106, v0
	v_mov_b32_e32 v107, v0
	v_mov_b32_e32 v108, v0
	v_mov_b32_e32 v109, v0
	v_mov_b32_e32 v110, v0
	v_mov_b32_e32 v111, v0
	v_mov_b32_e32 v120, v0
	v_mov_b32_e32 v121, v0
	v_mov_b32_e32 v122, v0
	v_mov_b32_e32 v123, v0
	v_mov_b32_e32 v124, v0
	v_mov_b32_e32 v125, v0
	v_mov_b32_e32 v126, v0
	v_mov_b32_e32 v127, v0
	s_branch .LBB0_623
	s_nop 0
	s_nop 0
	s_nop 0
	s_nop 0

; template <class Epi, class Sched, bool ALIGN_EPI = false, bool SP2 = false>
; __device__ __forceinline__ void gemm_phase(PG8_LAS unsigned char* lds, const Gemm g, const Sched& S, const Epi& E, const int wave_s) {
;     ...
;         const bool has_next = S.next(ui + 1, nxt);
;         const char* nA = has_next ? (const char*)g.A + (size_t)nxt.pm * tA : cA; const char* nB = has_next ? (const char*)g.Bt + (size_t)nxt.pn * tB : cB;
;     ...
; #pragma unroll
;         for (int a = 0; a < 2; ++a)
; #pragma unroll
;             for (int b = 0; b < 2; ++b)
; #pragma unroll
;                 for (int m = 0; m < 4; ++m)
; #pragma unroll
;                     for (int n = 0; n < 2; ++n) acc[a][b][m][n] = (f32x4){0.f, 0.f, 0.f, 0.f};
;         cur = nxt; cA = nA; cB = nB; ++ui;
.LBB0_695:
	s_ashr_i32 s49, s48, 31
	s_lshl_b64 s[8:9], s[48:49], 19
	s_add_u32 s50, s18, s8
	s_addc_u32 s51, s19, s9
	s_and_b64 s[8:9], s[6:7], exec
	s_cselect_b32 s8, s51, s65
	s_cselect_b32 s9, s50, s64
	s_ashr_i32 s47, s46, 31
	s_lshl_b64 s[58:59], s[46:47], 19
	s_add_u32 s58, s56, s58
	s_addc_u32 s59, s57, s59
	s_and_b64 s[68:69], s[6:7], exec
	s_cselect_b32 s47, s59, s67
	s_cselect_b32 s49, s58, s66
	s_add_u32 s64, s64, 0x40080
	s_addc_u32 s65, s65, 0
	s_add_u32 s61, s66, 0x100
	v_mov_b32_e32 v0, 0
	s_addc_u32 s77, s67, 0
	s_mov_b32 s78, -2
	s_waitcnt lgkmcnt(0)
	v_mov_b32_e32 v1, v0
	v_mov_b32_e32 v2, v0
	v_mov_b32_e32 v3, v0
	v_mov_b32_e32 v4, v0
	v_mov_b32_e32 v5, v0
	v_mov_b32_e32 v6, v0
	v_mov_b32_e32 v7, v0
	v_mov_b32_e32 v16, v0
	v_mov_b32_e32 v17, v0
	v_mov_b32_e32 v18, v0
	v_mov_b32_e32 v19, v0
	v_mov_b32_e32 v20, v0
	v_mov_b32_e32 v21, v0
	v_mov_b32_e32 v22, v0
	v_mov_b32_e32 v23, v0
	v_mov_b32_e32 v32, v0
	v_mov_b32_e32 v33, v0
	v_mov_b32_e32 v34, v0
	v_mov_b32_e32 v35, v0
	v_mov_b32_e32 v36, v0
	v_mov_b32_e32 v37, v0
	v_mov_b32_e32 v38, v0
	v_mov_b32_e32 v39, v0
	v_mov_b32_e32 v48, v0
	v_mov_b32_e32 v49, v0
	v_mov_b32_e32 v50, v0
	v_mov_b32_e32 v51, v0
	v_mov_b32_e32 v52, v0
	v_mov_b32_e32 v53, v0
	v_mov_b32_e32 v54, v0
	v_mov_b32_e32 v55, v0
	v_mov_b32_e32 v8, v0
	v_mov_b32_e32 v9, v0
	v_mov_b32_e32 v10, v0
	v_mov_b32_e32 v11, v0
	v_mov_b32_e32 v12, v0
	v_mov_b32_e32 v13, v0
	v_mov_b32_e32 v14, v0
	v_mov_b32_e32 v15, v0
	v_mov_b32_e32 v24, v0
	v_mov_b32_e32 v25, v0
	v_mov_b32_e32 v26, v0
	v_mov_b32_e32 v27, v0
	v_mov_b32_e32 v28, v0
	v_mov_b32_e32 v29, v0
	v_mov_b32_e32 v30, v0
	v_mov_b32_e32 v31, v0
	v_mov_b32_e32 v40, v0
	v_mov_b32_e32 v41, v0
	v_mov_b32_e32 v42, v0
	v_mov_b32_e32 v43, v0
	v_mov_b32_e32 v44, v0
	v_mov_b32_e32 v45, v0
	v_mov_b32_e32 v46, v0
	v_mov_b32_e32 v47, v0
	v_mov_b32_e32 v56, v0
	v_mov_b32_e32 v57, v0
	v_mov_b32_e32 v58, v0
	v_mov_b32_e32 v59, v0
	v_mov_b32_e32 v60, v0
	v_mov_b32_e32 v61, v0
	v_mov_b32_e32 v62, v0
	v_mov_b32_e32 v63, v0
	v_mov_b32_e32 v64, v0
	v_mov_b32_e32 v65, v0
	v_mov_b32_e32 v66, v0
	v_mov_b32_e32 v67, v0
	v_mov_b32_e32 v68, v0
	v_mov_b32_e32 v69, v0
	v_mov_b32_e32 v70, v0
	v_mov_b32_e32 v71, v0
	v_mov_b32_e32 v80, v0
	v_mov_b32_e32 v81, v0
	v_mov_b32_e32 v82, v0
	v_mov_b32_e32 v83, v0
	v_mov_b32_e32 v84, v0
	v_mov_b32_e32 v85, v0
	v_mov_b32_e32 v86, v0
	v_mov_b32_e32 v87, v0
	v_mov_b32_e32 v96, v0
	v_mov_b32_e32 v97, v0
	v_mov_b32_e32 v98, v0
	v_mov_b32_e32 v99, v0
	v_mov_b32_e32 v100, v0
	v_mov_b32_e32 v101, v0
	v_mov_b32_e32 v102, v0
	v_mov_b32_e32 v103, v0
	v_mov_b32_e32 v112, v0
	v_mov_b32_e32 v113, v0
	v_mov_b32_e32 v114, v0
	v_mov_b32_e32 v115, v0
	v_mov_b32_e32 v116, v0
	v_mov_b32_e32 v117, v0
	v_mov_b32_e32 v118, v0
	v_mov_b32_e32 v119, v0
	v_mov_b32_e32 v72, v0
	v_mov_b32_e32 v73, v0
	v_mov_b32_e32 v74, v0
	v_mov_b32_e32 v75, v0
	v_mov_b32_e32 v76, v0
	v_mov_b32_e32 v77, v0
	v_mov_b32_e32 v78, v0
	v_mov_b32_e32 v79, v0
	v_mov_b32_e32 v88, v0
	v_mov_b32_e32 v89, v0
	v_mov_b32_e32 v90, v0
	v_mov_b32_e32 v91, v0
	v_mov_b32_e32 v92, v0
	v_mov_b32_e32 v93, v0
	v_mov_b32_e32 v94, v0
	v_mov_b32_e32 v95, v0
	v_mov_b32_e32 v104, v0
	v_mov_b32_e32 v105, v0
	v_mov_b32_e32 v106, v0
	v_mov_b32_e32 v107, v0
	v_mov_b32_e32 v108, v0
	v_mov_b32_e32 v109, v0
	v_mov_b32_e32 v110, v0
	v_mov_b32_e32 v111, v0
	v_mov_b32_e32 v120, v0
	v_mov_b32_e32 v121, v0
	v_mov_b32_e32 v122, v0
	v_mov_b32_e32 v123, v0
	v_mov_b32_e32 v124, v0
	v_mov_b32_e32 v125, v0
	v_mov_b32_e32 v126, v0
	v_mov_b32_e32 v127, v0
	s_nop 0
	s_nop 0
	s_nop 0
	s_nop 0
	s_nop 0
	s_nop 0
	s_nop 0
	s_nop 0
	s_nop 0
	s_nop 0
	s_nop 0
	s_nop 0
	s_nop 0

; template <class Epi, class Sched, bool ALIGN_EPI = false, bool SP2 = false>
; __device__ __forceinline__ void gemm_phase(PG8_LAS unsigned char* lds, const Gemm g, const Sched& S, const Epi& E, const int wave_s) {
;     ...
;         const bool has_next = S.next(ui + 1, nxt);
;         const char* nA = has_next ? (const char*)g.A + (size_t)nxt.pm * tA : cA; const char* nB = has_next ? (const char*)g.Bt + (size_t)nxt.pn * tB : cB;
;     ...
; #pragma unroll
;         for (int a = 0; a < 2; ++a)
; #pragma unroll
;             for (int b = 0; b < 2; ++b)
; #pragma unroll
;                 for (int m = 0; m < 4; ++m)
; #pragma unroll
;                     for (int n = 0; n < 2; ++n) acc[a][b][m][n] = (f32x4){0.f, 0.f, 0.f, 0.f};
;         cur = nxt; cA = nA; cB = nB; ++ui;
.LBB0_781:
	s_ashr_i32 s45, s44, 31
	s_lshl_b64 s[46:47], s[44:45], 19
	s_add_u32 s46, s14, s46
	s_addc_u32 s47, s15, s47
	s_and_b64 s[48:49], s[4:5], exec
	s_cselect_b32 s9, s47, s59
	s_cselect_b32 s45, s46, s58
	s_ashr_i32 s43, s42, 31
	s_lshl_b64 s[48:49], s[42:43], 19
	s_add_u32 s48, s54, s48
	s_addc_u32 s49, s55, s49
	s_and_b64 s[72:73], s[4:5], exec
	s_cselect_b32 s43, s49, s57
	s_cselect_b32 s72, s48, s56
	v_lshl_add_u32 v144, s50, 8, v148
	s_add_u32 s50, s58, 0x40080
	s_addc_u32 s51, s59, 0
	v_ashrrev_i32_e32 v145, 31, v144
	s_add_u32 s73, s56, 0x100
	v_mov_b32_e32 v0, 0
	v_lshl_add_u64 v[146:147], v[144:145], 2, s[26:27]
	s_addc_u32 s74, s57, 0
	s_mov_b32 s75, -2
	v_mov_b32_e32 v1, v0
	v_mov_b32_e32 v2, v0
	v_mov_b32_e32 v3, v0
	v_mov_b32_e32 v4, v0
	v_mov_b32_e32 v5, v0
	v_mov_b32_e32 v6, v0
	v_mov_b32_e32 v7, v0
	v_mov_b32_e32 v16, v0
	v_mov_b32_e32 v17, v0
	v_mov_b32_e32 v18, v0
	v_mov_b32_e32 v19, v0
	v_mov_b32_e32 v20, v0
	v_mov_b32_e32 v21, v0
	v_mov_b32_e32 v22, v0
	v_mov_b32_e32 v23, v0
	v_mov_b32_e32 v32, v0
	v_mov_b32_e32 v33, v0
	v_mov_b32_e32 v34, v0
	v_mov_b32_e32 v35, v0
	v_mov_b32_e32 v36, v0
	v_mov_b32_e32 v37, v0
	v_mov_b32_e32 v38, v0
	v_mov_b32_e32 v39, v0
	v_mov_b32_e32 v48, v0
	v_mov_b32_e32 v49, v0
	v_mov_b32_e32 v50, v0
	v_mov_b32_e32 v51, v0
	v_mov_b32_e32 v52, v0
	v_mov_b32_e32 v53, v0
	v_mov_b32_e32 v54, v0
	v_mov_b32_e32 v55, v0
	v_mov_b32_e32 v8, v0
	v_mov_b32_e32 v9, v0
	v_mov_b32_e32 v10, v0
	v_mov_b32_e32 v11, v0
	v_mov_b32_e32 v12, v0
	v_mov_b32_e32 v13, v0
	v_mov_b32_e32 v14, v0
	v_mov_b32_e32 v15, v0
	v_mov_b32_e32 v24, v0
	v_mov_b32_e32 v25, v0
	v_mov_b32_e32 v26, v0
	v_mov_b32_e32 v27, v0
	v_mov_b32_e32 v28, v0
	v_mov_b32_e32 v29, v0
	v_mov_b32_e32 v30, v0
	v_mov_b32_e32 v31, v0
	v_mov_b32_e32 v40, v0
	v_mov_b32_e32 v41, v0
	v_mov_b32_e32 v42, v0
	v_mov_b32_e32 v43, v0
	v_mov_b32_e32 v44, v0
	v_mov_b32_e32 v45, v0
	v_mov_b32_e32 v46, v0
	v_mov_b32_e32 v47, v0
	v_mov_b32_e32 v56, v0
	v_mov_b32_e32 v57, v0
	v_mov_b32_e32 v58, v0
	v_mov_b32_e32 v59, v0
	v_mov_b32_e32 v60, v0
	v_mov_b32_e32 v61, v0
	v_mov_b32_e32 v62, v0
	v_mov_b32_e32 v63, v0
	v_mov_b32_e32 v64, v0
	v_mov_b32_e32 v65, v0
	v_mov_b32_e32 v66, v0
	v_mov_b32_e32 v67, v0
	v_mov_b32_e32 v68, v0
	v_mov_b32_e32 v69, v0
	v_mov_b32_e32 v70, v0
	v_mov_b32_e32 v71, v0
	v_mov_b32_e32 v80, v0
	v_mov_b32_e32 v81, v0
	v_mov_b32_e32 v82, v0
	v_mov_b32_e32 v83, v0
	v_mov_b32_e32 v84, v0
	v_mov_b32_e32 v85, v0
	v_mov_b32_e32 v86, v0
	v_mov_b32_e32 v87, v0
	v_mov_b32_e32 v96, v0
	v_mov_b32_e32 v97, v0
	v_mov_b32_e32 v98, v0
	v_mov_b32_e32 v99, v0
	v_mov_b32_e32 v100, v0
	v_mov_b32_e32 v101, v0
	v_mov_b32_e32 v102, v0
	v_mov_b32_e32 v103, v0
	v_mov_b32_e32 v112, v0
	v_mov_b32_e32 v113, v0
	v_mov_b32_e32 v114, v0
	v_mov_b32_e32 v115, v0
	v_mov_b32_e32 v116, v0
	v_mov_b32_e32 v117, v0
	v_mov_b32_e32 v118, v0
	v_mov_b32_e32 v119, v0
	v_mov_b32_e32 v72, v0
	v_mov_b32_e32 v73, v0
	v_mov_b32_e32 v74, v0
	v_mov_b32_e32 v75, v0
	v_mov_b32_e32 v76, v0
	v_mov_b32_e32 v77, v0
	v_mov_b32_e32 v78, v0
	v_mov_b32_e32 v79, v0
	v_mov_b32_e32 v88, v0
	v_mov_b32_e32 v89, v0
	v_mov_b32_e32 v90, v0
	v_mov_b32_e32 v91, v0
	v_mov_b32_e32 v92, v0
	v_mov_b32_e32 v93, v0
	v_mov_b32_e32 v94, v0
	v_mov_b32_e32 v95, v0
	v_mov_b32_e32 v104, v0
	v_mov_b32_e32 v105, v0
	v_mov_b32_e32 v106, v0
	v_mov_b32_e32 v107, v0
	v_mov_b32_e32 v108, v0
	v_mov_b32_e32 v109, v0
	v_mov_b32_e32 v110, v0
	v_mov_b32_e32 v111, v0
	v_mov_b32_e32 v120, v0
	v_mov_b32_e32 v121, v0
	v_mov_b32_e32 v122, v0
	v_mov_b32_e32 v123, v0
	v_mov_b32_e32 v124, v0
	v_mov_b32_e32 v125, v0
	v_mov_b32_e32 v126, v0
	v_mov_b32_e32 v127, v0
	s_branch .LBB0_783
	s_nop 0
	s_nop 0
	s_nop 0
	s_nop 0
	s_nop 0
	s_nop 0

; template <class Epi, class Sched, bool ALIGN_EPI = false, bool SP2 = false>
; __device__ __forceinline__ void gemm_phase(PG8_LAS unsigned char* lds, const Gemm g, const Sched& S, const Epi& E, const int wave_s) {
;     ...
;         const bool has_next = S.next(ui + 1, nxt);
;         const char* nA = has_next ? (const char*)g.A + (size_t)nxt.pm * tA : cA; const char* nB = has_next ? (const char*)g.Bt + (size_t)nxt.pn * tB : cB;
;     ...
; #pragma unroll
;         for (int a = 0; a < 2; ++a)
; #pragma unroll
;             for (int b = 0; b < 2; ++b)
; #pragma unroll
;                 for (int m = 0; m < 4; ++m)
; #pragma unroll
;                     for (int n = 0; n < 2; ++n) acc[a][b][m][n] = (f32x4){0.f, 0.f, 0.f, 0.f};
;         cur = nxt; cA = nA; cB = nB; ++ui;
.LBB0_855:
	s_ashr_i32 s39, s38, 31
	s_lshl_b64 s[8:9], s[38:39], 21
	s_add_u32 s40, s16, s8
	s_addc_u32 s41, s17, s9
	s_and_b64 s[8:9], s[4:5], exec
	s_cselect_b32 s8, s41, s49
	s_cselect_b32 s9, s40, s48
	s_ashr_i32 s37, s36, 31
	s_lshl_b64 s[42:43], s[36:37], 21
	s_add_u32 s42, s52, s42
	s_addc_u32 s43, s53, s43
	s_and_b64 s[54:55], s[4:5], exec
	s_cselect_b32 s37, s43, s51
	s_cselect_b32 s39, s42, s50
	s_add_u32 s48, s48, 0x100080
	s_addc_u32 s49, s49, 0
	s_add_u32 s45, s50, 0x100
	v_mov_b32_e32 v0, 0
	s_addc_u32 s63, s51, 0
	s_mov_b32 s64, -2
	s_waitcnt lgkmcnt(0)
	v_mov_b32_e32 v1, v0
	v_mov_b32_e32 v2, v0
	v_mov_b32_e32 v3, v0
	v_mov_b32_e32 v4, v0
	v_mov_b32_e32 v5, v0
	v_mov_b32_e32 v6, v0
	v_mov_b32_e32 v7, v0
	v_mov_b32_e32 v16, v0
	v_mov_b32_e32 v17, v0
	v_mov_b32_e32 v18, v0
	v_mov_b32_e32 v19, v0
	v_mov_b32_e32 v20, v0
	v_mov_b32_e32 v21, v0
	v_mov_b32_e32 v22, v0
	v_mov_b32_e32 v23, v0
	v_mov_b32_e32 v32, v0
	v_mov_b32_e32 v33, v0
	v_mov_b32_e32 v34, v0
	v_mov_b32_e32 v35, v0
	v_mov_b32_e32 v36, v0
	v_mov_b32_e32 v37, v0
	v_mov_b32_e32 v38, v0
	v_mov_b32_e32 v39, v0
	v_mov_b32_e32 v48, v0
	v_mov_b32_e32 v49, v0
	v_mov_b32_e32 v50, v0
	v_mov_b32_e32 v51, v0
	v_mov_b32_e32 v52, v0
	v_mov_b32_e32 v53, v0
	v_mov_b32_e32 v54, v0
	v_mov_b32_e32 v55, v0
	v_mov_b32_e32 v8, v0
	v_mov_b32_e32 v9, v0
	v_mov_b32_e32 v10, v0
	v_mov_b32_e32 v11, v0
	v_mov_b32_e32 v12, v0
	v_mov_b32_e32 v13, v0
	v_mov_b32_e32 v14, v0
	v_mov_b32_e32 v15, v0
	v_mov_b32_e32 v24, v0
	v_mov_b32_e32 v25, v0
	v_mov_b32_e32 v26, v0
	v_mov_b32_e32 v27, v0
	v_mov_b32_e32 v28, v0
	v_mov_b32_e32 v29, v0
	v_mov_b32_e32 v30, v0
	v_mov_b32_e32 v31, v0
	v_mov_b32_e32 v40, v0
	v_mov_b32_e32 v41, v0
	v_mov_b32_e32 v42, v0
	v_mov_b32_e32 v43, v0
	v_mov_b32_e32 v44, v0
	v_mov_b32_e32 v45, v0
	v_mov_b32_e32 v46, v0
	v_mov_b32_e32 v47, v0
	v_mov_b32_e32 v56, v0
	v_mov_b32_e32 v57, v0
	v_mov_b32_e32 v58, v0
	v_mov_b32_e32 v59, v0
	v_mov_b32_e32 v60, v0
	v_mov_b32_e32 v61, v0
	v_mov_b32_e32 v62, v0
	v_mov_b32_e32 v63, v0
	v_mov_b32_e32 v64, v0
	v_mov_b32_e32 v65, v0
	v_mov_b32_e32 v66, v0
	v_mov_b32_e32 v67, v0
	v_mov_b32_e32 v68, v0
	v_mov_b32_e32 v69, v0
	v_mov_b32_e32 v70, v0
	v_mov_b32_e32 v71, v0
	v_mov_b32_e32 v80, v0
	v_mov_b32_e32 v81, v0
	v_mov_b32_e32 v82, v0
	v_mov_b32_e32 v83, v0
	v_mov_b32_e32 v84, v0
	v_mov_b32_e32 v85, v0
	v_mov_b32_e32 v86, v0
	v_mov_b32_e32 v87, v0
	v_mov_b32_e32 v96, v0
	v_mov_b32_e32 v97, v0
	v_mov_b32_e32 v98, v0
	v_mov_b32_e32 v99, v0
	v_mov_b32_e32 v100, v0
	v_mov_b32_e32 v101, v0
	v_mov_b32_e32 v102, v0
	v_mov_b32_e32 v103, v0
	v_mov_b32_e32 v112, v0
	v_mov_b32_e32 v113, v0
	v_mov_b32_e32 v114, v0
	v_mov_b32_e32 v115, v0
	v_mov_b32_e32 v116, v0
	v_mov_b32_e32 v117, v0
	v_mov_b32_e32 v118, v0
	v_mov_b32_e32 v119, v0
	v_mov_b32_e32 v72, v0
	v_mov_b32_e32 v73, v0
	v_mov_b32_e32 v74, v0
	v_mov_b32_e32 v75, v0
	v_mov_b32_e32 v76, v0
	v_mov_b32_e32 v77, v0
	v_mov_b32_e32 v78, v0
	v_mov_b32_e32 v79, v0
	v_mov_b32_e32 v88, v0
	v_mov_b32_e32 v89, v0
	v_mov_b32_e32 v90, v0
	v_mov_b32_e32 v91, v0
	v_mov_b32_e32 v92, v0
	v_mov_b32_e32 v93, v0
	v_mov_b32_e32 v94, v0
	v_mov_b32_e32 v95, v0
	v_mov_b32_e32 v104, v0
	v_mov_b32_e32 v105, v0
	v_mov_b32_e32 v106, v0
	v_mov_b32_e32 v107, v0
	v_mov_b32_e32 v108, v0
	v_mov_b32_e32 v109, v0
	v_mov_b32_e32 v110, v0
	v_mov_b32_e32 v111, v0
	v_mov_b32_e32 v120, v0
	v_mov_b32_e32 v121, v0
	v_mov_b32_e32 v122, v0
	v_mov_b32_e32 v123, v0
	v_mov_b32_e32 v124, v0
	v_mov_b32_e32 v125, v0
	v_mov_b32_e32 v126, v0
	v_mov_b32_e32 v127, v0
	s_nop 0
	s_nop 0
